# baseline (speedup 1.0000x reference)
; __device__ __forceinline__ float ss_read(const float* ss, int row, int fq) { const f32x4 a = *(const f32x4*)(ss + (unsigned)row * 32 + fq * 8), b = *(const f32x4*)(ss + (unsigned)row * 32 + fq * 8 + 4);
;     float s = ((a[0] + a[1]) + (a[2] + a[3])) + ((b[0] + b[1]) + (b[2] + b[3])); s += __shfl_xor(s, 16); s += __shfl_xor(s, 32); return s; }
;     __device__ __forceinline__ void operator()(const f32x4 (&acc)[2][2][4][2], const Unit& u, int wr, int wc, int fr_, int fq_) const {
;         int fr = fr_, fq = fq_; asm volatile("" : "+v"(fr), "+v"(fq));
;         const int tile = u.pn, row0 = u.pm * BM + wr * 64 + fr, j0 = wc * 32 + 8 * fq;
;         float rv[2][4];
; #pragma unroll
;         for (int ai = 0; ai < 2; ++ai)
; #pragma unroll
;             for (int m = 0; m < 4; ++m) rv[ai][m] = 1.0f / sqrtf(ss_read(ss, row0 + ai * HALF + m * 16, fq) * (1.0f / 2048.0f) + 1e-6f);
.LBB0_132:
	s_cmp_eq_u32 s10, s101
	s_cbranch_scc1 .Lrv1_hit
	v_and_b32_e32 v131, 64, v222
	v_xor_b32_e32 v130, 16, v222
	v_add_u32_e32 v131, 64, v131
	v_cmp_lt_i32_e32 vcc, v130, v131
	s_nop 1
	v_cndmask_b32_e32 v130, v222, v130, vcc
	v_lshlrev_b32_e32 v216, 2, v130
	v_xor_b32_e32 v130, 32, v222
	v_cmp_lt_i32_e32 vcc, v130, v131
	s_nop 1
	v_cndmask_b32_e32 v130, v222, v130, vcc
	v_lshlrev_b32_e32 v217, 2, v130
	s_lshl_b32 s0, s10, 8
	s_add_i32 s0, s0, s78
	v_add_u32_e32 v130, s0, v176
	v_lshlrev_b32_e32 v128, 7, v130
	v_lshl_add_u32 v128, v177, 5, v128
	v_mov_b32_e32 v129, v193
	v_lshl_add_u64 v[128:129], v[128:129], 0, s[60:61]
	global_load_dwordx4 v[164:167], v[128:129], off
	global_load_dwordx4 v[168:171], v[128:129], off offset:16
	s_nop 0
	s_mov_b32 s0, 0x800
	s_mov_b32 s1, 0
	v_lshl_add_u64 v[214:215], v[128:129], 0, s[0:1]
	global_load_dwordx4 v[172:175], v[214:215], off
	global_load_dwordx4 v[180:183], v[214:215], off offset:16
	s_nop 0
	s_mov_b32 s0, 0x1000
	s_mov_b32 s1, 0
	v_lshl_add_u64 v[214:215], v[128:129], 0, s[0:1]
	global_load_dwordx4 v[184:187], v[214:215], off
	global_load_dwordx4 v[188:191], v[214:215], off offset:16
	s_nop 0
	s_mov_b32 s0, 0x1800
	s_mov_b32 s1, 0
	v_lshl_add_u64 v[214:215], v[128:129], 0, s[0:1]
	global_load_dwordx4 v[206:209], v[214:215], off
	global_load_dwordx4 v[210:213], v[214:215], off offset:16
	s_nop 0
	s_waitcnt vmcnt(6)
	v_add_f32_e32 v130, v168, v169
	v_add_f32_e32 v131, v164, v165
	v_add_f32_e32 v132, v166, v167
	v_add_f32_e32 v133, v170, v171
	v_add_f32_e32 v131, v131, v132
	v_add_f32_e32 v130, v130, v133
	v_add_f32_e32 v130, v131, v130
	ds_bpermute_b32 v131, v216, v130
	s_waitcnt lgkmcnt(0)
	v_add_f32_e32 v130, v130, v131
	ds_bpermute_b32 v131, v217, v130
	s_waitcnt lgkmcnt(0)
	v_add_f32_e32 v130, v130, v131
	v_fmamk_f32 v130, v130, 0x3a000000, v225
	v_cmp_gt_f32_e32 vcc, s20, v130
	v_mul_f32_e32 v131, 0x4f800000, v130
	s_nop 0
	v_cndmask_b32_e32 v130, v130, v131, vcc
	v_sqrt_f32_e32 v131, v130
	s_nop 0
	v_add_u32_e32 v132, -1, v131
	v_fma_f32 v133, -v132, v131, v130
	v_cmp_ge_f32_e64 s[0:1], 0, v133
	v_add_u32_e32 v133, 1, v131
	s_nop 0
	v_cndmask_b32_e64 v132, v131, v132, s[0:1]
	v_fma_f32 v131, -v133, v131, v130
	v_cmp_lt_f32_e64 s[0:1], 0, v131
	s_nop 1
	v_cndmask_b32_e64 v131, v132, v133, s[0:1]
	v_mul_f32_e32 v132, 0x37800000, v131
	v_cndmask_b32_e32 v131, v131, v132, vcc
	v_cmp_class_f32_e32 vcc, v130, v226
	s_nop 1
	v_cndmask_b32_e32 v130, v131, v130, vcc
	v_div_scale_f32 v131, s[0:1], v130, v130, 1.0
	v_rcp_f32_e32 v132, v131
	s_nop 0
	v_fma_f32 v133, -v131, v132, 1.0
	v_fmac_f32_e32 v132, v133, v132
	v_div_scale_f32 v133, vcc, 1.0, v130, 1.0
	v_mul_f32_e32 v134, v133, v132
	v_fma_f32 v135, -v131, v134, v133
	v_fmac_f32_e32 v134, v135, v132
	v_fma_f32 v131, -v131, v134, v133
	v_div_fmas_f32 v131, v131, v132, v134
	v_div_fixup_f32 v246, v131, v130, 1.0
	s_waitcnt vmcnt(4)
	v_add_f32_e32 v130, v180, v181
	v_add_f32_e32 v131, v172, v173
	v_add_f32_e32 v132, v174, v175
	v_add_f32_e32 v133, v182, v183
	v_add_f32_e32 v131, v131, v132
	v_add_f32_e32 v130, v130, v133
	v_add_f32_e32 v130, v131, v130
	ds_bpermute_b32 v131, v216, v130
	s_waitcnt lgkmcnt(0)
	v_add_f32_e32 v130, v130, v131
	ds_bpermute_b32 v131, v217, v130
	s_waitcnt lgkmcnt(0)
	v_add_f32_e32 v130, v130, v131
	v_fmamk_f32 v130, v130, 0x3a000000, v225
	v_cmp_gt_f32_e32 vcc, s20, v130
	v_mul_f32_e32 v131, 0x4f800000, v130
	s_nop 0
	v_cndmask_b32_e32 v130, v130, v131, vcc
	v_sqrt_f32_e32 v131, v130
	s_nop 0
	v_add_u32_e32 v132, -1, v131
	v_fma_f32 v133, -v132, v131, v130
	v_cmp_ge_f32_e64 s[0:1], 0, v133
	v_add_u32_e32 v133, 1, v131
	s_nop 0
	v_cndmask_b32_e64 v132, v131, v132, s[0:1]
	v_fma_f32 v131, -v133, v131, v130
	v_cmp_lt_f32_e64 s[0:1], 0, v131
	s_nop 1
	v_cndmask_b32_e64 v131, v132, v133, s[0:1]
	v_mul_f32_e32 v132, 0x37800000, v131
	v_cndmask_b32_e32 v131, v131, v132, vcc
	v_cmp_class_f32_e32 vcc, v130, v226
	s_nop 1
	v_cndmask_b32_e32 v130, v131, v130, vcc
	v_div_scale_f32 v131, s[0:1], v130, v130, 1.0
	v_rcp_f32_e32 v132, v131
	s_nop 0
	v_fma_f32 v133, -v131, v132, 1.0
	v_fmac_f32_e32 v132, v133, v132
	v_div_scale_f32 v133, vcc, 1.0, v130, 1.0
	v_mul_f32_e32 v134, v133, v132
	v_fma_f32 v135, -v131, v134, v133
	v_fmac_f32_e32 v134, v135, v132
	v_fma_f32 v131, -v131, v134, v133
	v_div_fmas_f32 v131, v131, v132, v134
	v_div_fixup_f32 v247, v131, v130, 1.0
	s_waitcnt vmcnt(2)
	v_add_f32_e32 v130, v188, v189
	v_add_f32_e32 v131, v184, v185
	v_add_f32_e32 v132, v186, v187
	v_add_f32_e32 v133, v190, v191
	v_add_f32_e32 v131, v131, v132
	v_add_f32_e32 v130, v130, v133
	v_add_f32_e32 v130, v131, v130
	ds_bpermute_b32 v131, v216, v130
	s_waitcnt lgkmcnt(0)
	v_add_f32_e32 v130, v130, v131
	ds_bpermute_b32 v131, v217, v130
	s_waitcnt lgkmcnt(0)
	v_add_f32_e32 v130, v130, v131
	v_fmamk_f32 v130, v130, 0x3a000000, v225
	v_cmp_gt_f32_e32 vcc, s20, v130
	v_mul_f32_e32 v131, 0x4f800000, v130
	s_nop 0
	v_cndmask_b32_e32 v130, v130, v131, vcc
	v_sqrt_f32_e32 v131, v130
	s_nop 0
	v_add_u32_e32 v132, -1, v131
	v_fma_f32 v133, -v132, v131, v130
	v_cmp_ge_f32_e64 s[0:1], 0, v133
	v_add_u32_e32 v133, 1, v131
	s_nop 0
	v_cndmask_b32_e64 v132, v131, v132, s[0:1]
	v_fma_f32 v131, -v133, v131, v130
	v_cmp_lt_f32_e64 s[0:1], 0, v131
	s_nop 1
	v_cndmask_b32_e64 v131, v132, v133, s[0:1]
	v_mul_f32_e32 v132, 0x37800000, v131
	v_cndmask_b32_e32 v131, v131, v132, vcc
	v_cmp_class_f32_e32 vcc, v130, v226
	s_nop 1
	v_cndmask_b32_e32 v130, v131, v130, vcc
	v_div_scale_f32 v131, s[0:1], v130, v130, 1.0
	v_rcp_f32_e32 v132, v131
	s_nop 0
	v_fma_f32 v133, -v131, v132, 1.0
	v_fmac_f32_e32 v132, v133, v132
	v_div_scale_f32 v133, vcc, 1.0, v130, 1.0
	v_mul_f32_e32 v134, v133, v132
	v_fma_f32 v135, -v131, v134, v133
	v_fmac_f32_e32 v134, v135, v132
	v_fma_f32 v131, -v131, v134, v133
	v_div_fmas_f32 v131, v131, v132, v134
	v_div_fixup_f32 v248, v131, v130, 1.0
	s_waitcnt vmcnt(0)
; __device__ __forceinline__ float ss_read(const float* ss, int row, int fq) { const f32x4 a = *(const f32x4*)(ss + (unsigned)row * 32 + fq * 8), b = *(const f32x4*)(ss + (unsigned)row * 32 + fq * 8 + 4);
;     float s = ((a[0] + a[1]) + (a[2] + a[3])) + ((b[0] + b[1]) + (b[2] + b[3])); s += __shfl_xor(s, 16); s += __shfl_xor(s, 32); return s; }
;     __device__ __forceinline__ void operator()(const f32x4 (&acc)[2][2][4][2], const Unit& u, int wr, int wc, int fr_, int fq_) const {
;         int fr = fr_, fq = fq_; asm volatile("" : "+v"(fr), "+v"(fq));
;         const int tile = u.pn, row0 = u.pm * BM + wr * 64 + fr, j0 = wc * 32 + 8 * fq;
;         float rv[2][4];
; #pragma unroll
;         for (int ai = 0; ai < 2; ++ai)
; #pragma unroll
;             for (int m = 0; m < 4; ++m) rv[ai][m] = 1.0f / sqrtf(ss_read(ss, row0 + ai * HALF + m * 16, fq) * (1.0f / 2048.0f) + 1e-6f);
	v_add_f32_e32 v130, v210, v211
	v_add_f32_e32 v131, v206, v207
	v_add_f32_e32 v132, v208, v209
	v_add_f32_e32 v133, v212, v213
	v_add_f32_e32 v131, v131, v132
	v_add_f32_e32 v130, v130, v133
	v_add_f32_e32 v130, v131, v130
	ds_bpermute_b32 v131, v216, v130
	s_waitcnt lgkmcnt(0)
	v_add_f32_e32 v130, v130, v131
	ds_bpermute_b32 v131, v217, v130
	s_waitcnt lgkmcnt(0)
	v_add_f32_e32 v130, v130, v131
	v_fmamk_f32 v130, v130, 0x3a000000, v225
	v_cmp_gt_f32_e32 vcc, s20, v130
	v_mul_f32_e32 v131, 0x4f800000, v130
	s_nop 0
	v_cndmask_b32_e32 v130, v130, v131, vcc
	v_sqrt_f32_e32 v131, v130
	s_nop 0
	v_add_u32_e32 v132, -1, v131
	v_fma_f32 v133, -v132, v131, v130
	v_cmp_ge_f32_e64 s[0:1], 0, v133
	v_add_u32_e32 v133, 1, v131
	s_nop 0
	v_cndmask_b32_e64 v132, v131, v132, s[0:1]
	v_fma_f32 v131, -v133, v131, v130
	v_cmp_lt_f32_e64 s[0:1], 0, v131
	s_nop 1
	v_cndmask_b32_e64 v131, v132, v133, s[0:1]
	v_mul_f32_e32 v132, 0x37800000, v131
	v_cndmask_b32_e32 v131, v131, v132, vcc
	v_cmp_class_f32_e32 vcc, v130, v226
	s_nop 1
	v_cndmask_b32_e32 v130, v131, v130, vcc
	v_div_scale_f32 v131, s[0:1], v130, v130, 1.0
	v_rcp_f32_e32 v132, v131
	s_nop 0
	v_fma_f32 v133, -v131, v132, 1.0
	v_fmac_f32_e32 v132, v133, v132
	v_div_scale_f32 v133, vcc, 1.0, v130, 1.0
	v_mul_f32_e32 v134, v133, v132
	v_fma_f32 v135, -v131, v134, v133
	v_fmac_f32_e32 v134, v135, v132
	v_fma_f32 v131, -v131, v134, v133
	v_div_fmas_f32 v131, v131, v132, v134
	v_div_fixup_f32 v249, v131, v130, 1.0
	s_mov_b32 s0, 0x4000
	s_mov_b32 s1, 0
	v_lshl_add_u64 v[214:215], v[128:129], 0, s[0:1]
	global_load_dwordx4 v[164:167], v[214:215], off
	global_load_dwordx4 v[168:171], v[214:215], off offset:16
	s_nop 0
	s_mov_b32 s0, 0x4800
	s_mov_b32 s1, 0
	v_lshl_add_u64 v[214:215], v[128:129], 0, s[0:1]
	global_load_dwordx4 v[172:175], v[214:215], off
	global_load_dwordx4 v[180:183], v[214:215], off offset:16
	s_nop 0
	s_mov_b32 s0, 0x5000
	s_mov_b32 s1, 0
	v_lshl_add_u64 v[214:215], v[128:129], 0, s[0:1]
	global_load_dwordx4 v[184:187], v[214:215], off
	global_load_dwordx4 v[188:191], v[214:215], off offset:16
	s_nop 0
	s_mov_b32 s0, 0x5800
	s_mov_b32 s1, 0
	v_lshl_add_u64 v[214:215], v[128:129], 0, s[0:1]
	global_load_dwordx4 v[206:209], v[214:215], off
	global_load_dwordx4 v[210:213], v[214:215], off offset:16
	s_nop 0
	s_waitcnt vmcnt(6)
	v_add_f32_e32 v130, v168, v169
	v_add_f32_e32 v131, v164, v165
	v_add_f32_e32 v132, v166, v167
	v_add_f32_e32 v133, v170, v171
	v_add_f32_e32 v131, v131, v132
	v_add_f32_e32 v130, v130, v133
	v_add_f32_e32 v130, v131, v130
	ds_bpermute_b32 v131, v216, v130
	s_waitcnt lgkmcnt(0)
	v_add_f32_e32 v130, v130, v131
	ds_bpermute_b32 v131, v217, v130
	s_waitcnt lgkmcnt(0)
	v_add_f32_e32 v130, v130, v131
	v_fmamk_f32 v130, v130, 0x3a000000, v225
	v_cmp_gt_f32_e32 vcc, s20, v130
	v_mul_f32_e32 v131, 0x4f800000, v130
	s_nop 0
	v_cndmask_b32_e32 v130, v130, v131, vcc
	v_sqrt_f32_e32 v131, v130
	s_nop 0
	v_add_u32_e32 v132, -1, v131
	v_fma_f32 v133, -v132, v131, v130
	v_cmp_ge_f32_e64 s[0:1], 0, v133
	v_add_u32_e32 v133, 1, v131
	s_nop 0
	v_cndmask_b32_e64 v132, v131, v132, s[0:1]
	v_fma_f32 v131, -v133, v131, v130
	v_cmp_lt_f32_e64 s[0:1], 0, v131
	s_nop 1
	v_cndmask_b32_e64 v131, v132, v133, s[0:1]
	v_mul_f32_e32 v132, 0x37800000, v131
	v_cndmask_b32_e32 v131, v131, v132, vcc
	v_cmp_class_f32_e32 vcc, v130, v226
	s_nop 1
	v_cndmask_b32_e32 v130, v131, v130, vcc
	v_div_scale_f32 v131, s[0:1], v130, v130, 1.0
	v_rcp_f32_e32 v132, v131
	s_nop 0
	v_fma_f32 v133, -v131, v132, 1.0
	v_fmac_f32_e32 v132, v133, v132
	v_div_scale_f32 v133, vcc, 1.0, v130, 1.0
	v_mul_f32_e32 v134, v133, v132
	v_fma_f32 v135, -v131, v134, v133
	v_fmac_f32_e32 v134, v135, v132
	v_fma_f32 v131, -v131, v134, v133
	v_div_fmas_f32 v131, v131, v132, v134
	v_div_fixup_f32 v250, v131, v130, 1.0
	s_waitcnt vmcnt(4)
	v_add_f32_e32 v130, v180, v181
	v_add_f32_e32 v131, v172, v173
	v_add_f32_e32 v132, v174, v175
	v_add_f32_e32 v133, v182, v183
	v_add_f32_e32 v131, v131, v132
	v_add_f32_e32 v130, v130, v133
	v_add_f32_e32 v130, v131, v130
	ds_bpermute_b32 v131, v216, v130
	s_waitcnt lgkmcnt(0)
	v_add_f32_e32 v130, v130, v131
	ds_bpermute_b32 v131, v217, v130
	s_waitcnt lgkmcnt(0)
; __device__ __forceinline__ float ss_read(const float* ss, int row, int fq) { const f32x4 a = *(const f32x4*)(ss + (unsigned)row * 32 + fq * 8), b = *(const f32x4*)(ss + (unsigned)row * 32 + fq * 8 + 4);
;     float s = ((a[0] + a[1]) + (a[2] + a[3])) + ((b[0] + b[1]) + (b[2] + b[3])); s += __shfl_xor(s, 16); s += __shfl_xor(s, 32); return s; }
;     __device__ __forceinline__ void operator()(const f32x4 (&acc)[2][2][4][2], const Unit& u, int wr, int wc, int fr_, int fq_) const {
;         int fr = fr_, fq = fq_; asm volatile("" : "+v"(fr), "+v"(fq));
;         const int tile = u.pn, row0 = u.pm * BM + wr * 64 + fr, j0 = wc * 32 + 8 * fq;
;         float rv[2][4];
; #pragma unroll
;         for (int ai = 0; ai < 2; ++ai)
; #pragma unroll
;             for (int m = 0; m < 4; ++m) rv[ai][m] = 1.0f / sqrtf(ss_read(ss, row0 + ai * HALF + m * 16, fq) * (1.0f / 2048.0f) + 1e-6f);
	v_add_f32_e32 v130, v130, v131
	v_fmamk_f32 v130, v130, 0x3a000000, v225
	v_cmp_gt_f32_e32 vcc, s20, v130
	v_mul_f32_e32 v131, 0x4f800000, v130
	s_nop 0
	v_cndmask_b32_e32 v130, v130, v131, vcc
	v_sqrt_f32_e32 v131, v130
	s_nop 0
	v_add_u32_e32 v132, -1, v131
	v_fma_f32 v133, -v132, v131, v130
	v_cmp_ge_f32_e64 s[0:1], 0, v133
	v_add_u32_e32 v133, 1, v131
	s_nop 0
	v_cndmask_b32_e64 v132, v131, v132, s[0:1]
	v_fma_f32 v131, -v133, v131, v130
	v_cmp_lt_f32_e64 s[0:1], 0, v131
	s_nop 1
	v_cndmask_b32_e64 v131, v132, v133, s[0:1]
	v_mul_f32_e32 v132, 0x37800000, v131
	v_cndmask_b32_e32 v131, v131, v132, vcc
	v_cmp_class_f32_e32 vcc, v130, v226
	s_nop 1
	v_cndmask_b32_e32 v130, v131, v130, vcc
	v_div_scale_f32 v131, s[0:1], v130, v130, 1.0
	v_rcp_f32_e32 v132, v131
	s_nop 0
	v_fma_f32 v133, -v131, v132, 1.0
	v_fmac_f32_e32 v132, v133, v132
	v_div_scale_f32 v133, vcc, 1.0, v130, 1.0
	v_mul_f32_e32 v134, v133, v132
	v_fma_f32 v135, -v131, v134, v133
	v_fmac_f32_e32 v134, v135, v132
	v_fma_f32 v131, -v131, v134, v133
	v_div_fmas_f32 v131, v131, v132, v134
	v_div_fixup_f32 v251, v131, v130, 1.0
	s_waitcnt vmcnt(2)
	v_add_f32_e32 v130, v188, v189
	v_add_f32_e32 v131, v184, v185
	v_add_f32_e32 v132, v186, v187
	v_add_f32_e32 v133, v190, v191
	v_add_f32_e32 v131, v131, v132
	v_add_f32_e32 v130, v130, v133
	v_add_f32_e32 v130, v131, v130
	ds_bpermute_b32 v131, v216, v130
	s_waitcnt lgkmcnt(0)
	v_add_f32_e32 v130, v130, v131
	ds_bpermute_b32 v131, v217, v130
	s_waitcnt lgkmcnt(0)
	v_add_f32_e32 v130, v130, v131
	v_fmamk_f32 v130, v130, 0x3a000000, v225
	v_cmp_gt_f32_e32 vcc, s20, v130
	v_mul_f32_e32 v131, 0x4f800000, v130
	s_nop 0
	v_cndmask_b32_e32 v130, v130, v131, vcc
	v_sqrt_f32_e32 v131, v130
	s_nop 0
	v_add_u32_e32 v132, -1, v131
	v_fma_f32 v133, -v132, v131, v130
	v_cmp_ge_f32_e64 s[0:1], 0, v133
	v_add_u32_e32 v133, 1, v131
	s_nop 0
	v_cndmask_b32_e64 v132, v131, v132, s[0:1]
	v_fma_f32 v131, -v133, v131, v130
	v_cmp_lt_f32_e64 s[0:1], 0, v131
	s_nop 1
	v_cndmask_b32_e64 v131, v132, v133, s[0:1]
	v_mul_f32_e32 v132, 0x37800000, v131
	v_cndmask_b32_e32 v131, v131, v132, vcc
	v_cmp_class_f32_e32 vcc, v130, v226
	s_nop 1
	v_cndmask_b32_e32 v130, v131, v130, vcc
	v_div_scale_f32 v131, s[0:1], v130, v130, 1.0
	v_rcp_f32_e32 v132, v131
	s_nop 0
	v_fma_f32 v133, -v131, v132, 1.0
	v_fmac_f32_e32 v132, v133, v132
	v_div_scale_f32 v133, vcc, 1.0, v130, 1.0
	v_mul_f32_e32 v134, v133, v132
	v_fma_f32 v135, -v131, v134, v133
	v_fmac_f32_e32 v134, v135, v132
	v_fma_f32 v131, -v131, v134, v133
	v_div_fmas_f32 v131, v131, v132, v134
	v_div_fixup_f32 v236, v131, v130, 1.0
	s_waitcnt vmcnt(0)
	v_add_f32_e32 v130, v210, v211
	v_add_f32_e32 v131, v206, v207
	v_add_f32_e32 v132, v208, v209
	v_add_f32_e32 v133, v212, v213
	v_add_f32_e32 v131, v131, v132
	v_add_f32_e32 v130, v130, v133
	v_add_f32_e32 v130, v131, v130
	ds_bpermute_b32 v131, v216, v130
	s_waitcnt lgkmcnt(0)
	v_add_f32_e32 v130, v130, v131
	ds_bpermute_b32 v131, v217, v130
	s_waitcnt lgkmcnt(0)
	v_add_f32_e32 v130, v130, v131
	v_fmamk_f32 v130, v130, 0x3a000000, v225
	v_cmp_gt_f32_e32 vcc, s20, v130
	v_mul_f32_e32 v131, 0x4f800000, v130
	s_nop 0
	v_cndmask_b32_e32 v130, v130, v131, vcc
	v_sqrt_f32_e32 v131, v130
	s_nop 0
	v_add_u32_e32 v132, -1, v131
	v_fma_f32 v133, -v132, v131, v130
	v_cmp_ge_f32_e64 s[0:1], 0, v133
	v_add_u32_e32 v133, 1, v131
	s_nop 0
	v_cndmask_b32_e64 v132, v131, v132, s[0:1]
	v_fma_f32 v131, -v133, v131, v130
	v_cmp_lt_f32_e64 s[0:1], 0, v131
	s_nop 1
	v_cndmask_b32_e64 v131, v132, v133, s[0:1]
	v_mul_f32_e32 v132, 0x37800000, v131
	v_cndmask_b32_e32 v131, v131, v132, vcc
	v_cmp_class_f32_e32 vcc, v130, v226
	s_nop 1
	v_cndmask_b32_e32 v130, v131, v130, vcc
	v_div_scale_f32 v131, s[0:1], v130, v130, 1.0
	v_rcp_f32_e32 v132, v131
	s_nop 0
	v_fma_f32 v133, -v131, v132, 1.0
	v_fmac_f32_e32 v132, v133, v132
	v_div_scale_f32 v133, vcc, 1.0, v130, 1.0
	v_mul_f32_e32 v134, v133, v132
	v_fma_f32 v135, -v131, v134, v133
	v_fmac_f32_e32 v134, v135, v132
	v_fma_f32 v131, -v131, v134, v133
	v_div_fmas_f32 v131, v131, v132, v134
	v_div_fixup_f32 v237, v131, v130, 1.0
	s_mov_b32 s101, s10

; __device__ __forceinline__ float ss_read(const float* ss, int row, int fq) { const f32x4 a = *(const f32x4*)(ss + (unsigned)row * 32 + fq * 8), b = *(const f32x4*)(ss + (unsigned)row * 32 + fq * 8 + 4);
;     float s = ((a[0] + a[1]) + (a[2] + a[3])) + ((b[0] + b[1]) + (b[2] + b[3])); s += __shfl_xor(s, 16); s += __shfl_xor(s, 32); return s; }
;     __device__ __forceinline__ void operator()(const f32x4 (&acc)[2][2][4][2], const Unit& u, int wr, int wc, int fr_, int fq_) const {
;     ...
;                 f32x4 p0, p1; const float rv = 1.0f / sqrtf(ss_read(ss, row0 + ai * HALF + m * 16, fq) * (1.0f / 2048.0f) + 1e-6f);
.LBB0_733:
	s_cmp_eq_u32 s59, s101
	s_cbranch_scc1 .Lrv8_hit
	v_and_b32_e32 v141, 64, v222
	v_xor_b32_e32 v140, 16, v222
	v_add_u32_e32 v141, 64, v141
	v_cmp_lt_i32_e32 vcc, v140, v141
	s_nop 1
	v_cndmask_b32_e32 v140, v222, v140, vcc
	v_lshlrev_b32_e32 v156, 2, v140
	v_xor_b32_e32 v140, 32, v222
	v_cmp_lt_i32_e32 vcc, v140, v141
	s_nop 1
	v_cndmask_b32_e32 v140, v222, v140, vcc
	v_lshlrev_b32_e32 v157, 2, v140
	s_lshl_b32 s0, s59, 8
	s_add_i32 s0, s0, s39
	v_add_u32_e32 v140, s0, v149
	v_lshlrev_b32_e32 v146, 7, v140
	v_lshl_add_u32 v146, v150, 5, v146
	v_mov_b32_e32 v147, v193
	v_lshl_add_u64 v[146:147], v[146:147], 0, s[8:9]
	global_load_dwordx4 v[160:163], v[146:147], off
	global_load_dwordx4 v[164:167], v[146:147], off offset:16
	s_nop 0
	s_mov_b32 s0, 0x800
	s_mov_b32 s1, 0
	v_lshl_add_u64 v[154:155], v[146:147], 0, s[0:1]
	global_load_dwordx4 v[168:171], v[154:155], off
	global_load_dwordx4 v[172:175], v[154:155], off offset:16
	s_nop 0
	s_mov_b32 s0, 0x1000
	s_mov_b32 s1, 0
	v_lshl_add_u64 v[154:155], v[146:147], 0, s[0:1]
	global_load_dwordx4 v[176:179], v[154:155], off
	global_load_dwordx4 v[180:183], v[154:155], off offset:16
	s_nop 0
	s_mov_b32 s0, 0x1800
	s_mov_b32 s1, 0
	v_lshl_add_u64 v[154:155], v[146:147], 0, s[0:1]
	global_load_dwordx4 v[184:187], v[154:155], off
	global_load_dwordx4 v[188:191], v[154:155], off offset:16
	s_nop 0
	s_waitcnt vmcnt(6)
	v_add_f32_e32 v140, v164, v165
	v_add_f32_e32 v141, v160, v161
	v_add_f32_e32 v142, v162, v163
	v_add_f32_e32 v143, v166, v167
	v_add_f32_e32 v141, v141, v142
	v_add_f32_e32 v140, v140, v143
	v_add_f32_e32 v140, v141, v140
	ds_bpermute_b32 v141, v156, v140
	s_waitcnt lgkmcnt(0)
	v_add_f32_e32 v140, v140, v141
	ds_bpermute_b32 v141, v157, v140
	s_waitcnt lgkmcnt(0)
	v_add_f32_e32 v140, v140, v141
	v_fmamk_f32 v140, v140, 0x3a000000, v225
	v_cmp_gt_f32_e32 vcc, s20, v140
	v_mul_f32_e32 v141, 0x4f800000, v140
	s_nop 0
	v_cndmask_b32_e32 v140, v140, v141, vcc
	v_sqrt_f32_e32 v141, v140
	s_nop 0
	v_add_u32_e32 v142, -1, v141
	v_fma_f32 v143, -v142, v141, v140
	v_cmp_ge_f32_e64 s[0:1], 0, v143
	v_add_u32_e32 v143, 1, v141
	s_nop 0
	v_cndmask_b32_e64 v142, v141, v142, s[0:1]
	v_fma_f32 v141, -v143, v141, v140
	v_cmp_lt_f32_e64 s[0:1], 0, v141
	s_nop 1
	v_cndmask_b32_e64 v141, v142, v143, s[0:1]
	v_mul_f32_e32 v142, 0x37800000, v141
	v_cndmask_b32_e32 v141, v141, v142, vcc
	v_cmp_class_f32_e32 vcc, v140, v226
	s_nop 1
	v_cndmask_b32_e32 v140, v141, v140, vcc
	v_div_scale_f32 v141, s[0:1], v140, v140, 1.0
	v_rcp_f32_e32 v142, v141
	s_nop 0
	v_fma_f32 v143, -v141, v142, 1.0
	v_fmac_f32_e32 v142, v143, v142
	v_div_scale_f32 v143, vcc, 1.0, v140, 1.0
	v_mul_f32_e32 v144, v143, v142
	v_fma_f32 v145, -v141, v144, v143
	v_fmac_f32_e32 v144, v145, v142
	v_fma_f32 v141, -v141, v144, v143
	v_div_fmas_f32 v141, v141, v142, v144
	v_div_fixup_f32 v246, v141, v140, 1.0
	s_waitcnt vmcnt(4)
	v_add_f32_e32 v140, v172, v173
	v_add_f32_e32 v141, v168, v169
	v_add_f32_e32 v142, v170, v171
	v_add_f32_e32 v143, v174, v175
	v_add_f32_e32 v141, v141, v142
	v_add_f32_e32 v140, v140, v143
	v_add_f32_e32 v140, v141, v140
	ds_bpermute_b32 v141, v156, v140
	s_waitcnt lgkmcnt(0)
	v_add_f32_e32 v140, v140, v141
	ds_bpermute_b32 v141, v157, v140
	s_waitcnt lgkmcnt(0)
	v_add_f32_e32 v140, v140, v141
	v_fmamk_f32 v140, v140, 0x3a000000, v225
	v_cmp_gt_f32_e32 vcc, s20, v140
	v_mul_f32_e32 v141, 0x4f800000, v140
	s_nop 0
	v_cndmask_b32_e32 v140, v140, v141, vcc
	v_sqrt_f32_e32 v141, v140
	s_nop 0
	v_add_u32_e32 v142, -1, v141
	v_fma_f32 v143, -v142, v141, v140
	v_cmp_ge_f32_e64 s[0:1], 0, v143
	v_add_u32_e32 v143, 1, v141
	s_nop 0
	v_cndmask_b32_e64 v142, v141, v142, s[0:1]
	v_fma_f32 v141, -v143, v141, v140
	v_cmp_lt_f32_e64 s[0:1], 0, v141
	s_nop 1
	v_cndmask_b32_e64 v141, v142, v143, s[0:1]
	v_mul_f32_e32 v142, 0x37800000, v141
	v_cndmask_b32_e32 v141, v141, v142, vcc
	v_cmp_class_f32_e32 vcc, v140, v226
	s_nop 1
	v_cndmask_b32_e32 v140, v141, v140, vcc
	v_div_scale_f32 v141, s[0:1], v140, v140, 1.0
	v_rcp_f32_e32 v142, v141
	s_nop 0
	v_fma_f32 v143, -v141, v142, 1.0
	v_fmac_f32_e32 v142, v143, v142
	v_div_scale_f32 v143, vcc, 1.0, v140, 1.0
	v_mul_f32_e32 v144, v143, v142
	v_fma_f32 v145, -v141, v144, v143
	v_fmac_f32_e32 v144, v145, v142
	v_fma_f32 v141, -v141, v144, v143
	v_div_fmas_f32 v141, v141, v142, v144
	v_div_fixup_f32 v247, v141, v140, 1.0
	s_waitcnt vmcnt(2)
	v_add_f32_e32 v140, v180, v181
	v_add_f32_e32 v141, v176, v177
	v_add_f32_e32 v142, v178, v179
	v_add_f32_e32 v143, v182, v183
	v_add_f32_e32 v141, v141, v142
	v_add_f32_e32 v140, v140, v143
	v_add_f32_e32 v140, v141, v140
	ds_bpermute_b32 v141, v156, v140
	s_waitcnt lgkmcnt(0)
	v_add_f32_e32 v140, v140, v141
	ds_bpermute_b32 v141, v157, v140
	s_waitcnt lgkmcnt(0)
	v_add_f32_e32 v140, v140, v141
	v_fmamk_f32 v140, v140, 0x3a000000, v225
	v_cmp_gt_f32_e32 vcc, s20, v140
	v_mul_f32_e32 v141, 0x4f800000, v140
	s_nop 0
	v_cndmask_b32_e32 v140, v140, v141, vcc
	v_sqrt_f32_e32 v141, v140
	s_nop 0
	v_add_u32_e32 v142, -1, v141
	v_fma_f32 v143, -v142, v141, v140
	v_cmp_ge_f32_e64 s[0:1], 0, v143
	v_add_u32_e32 v143, 1, v141
	s_nop 0
	v_cndmask_b32_e64 v142, v141, v142, s[0:1]
	v_fma_f32 v141, -v143, v141, v140
	v_cmp_lt_f32_e64 s[0:1], 0, v141
	s_nop 1
	v_cndmask_b32_e64 v141, v142, v143, s[0:1]
	v_mul_f32_e32 v142, 0x37800000, v141
	v_cndmask_b32_e32 v141, v141, v142, vcc
	v_cmp_class_f32_e32 vcc, v140, v226
	s_nop 1
	v_cndmask_b32_e32 v140, v141, v140, vcc
	v_div_scale_f32 v141, s[0:1], v140, v140, 1.0
	v_rcp_f32_e32 v142, v141
	s_nop 0
	v_fma_f32 v143, -v141, v142, 1.0
	v_fmac_f32_e32 v142, v143, v142
	v_div_scale_f32 v143, vcc, 1.0, v140, 1.0
	v_mul_f32_e32 v144, v143, v142
	v_fma_f32 v145, -v141, v144, v143
	v_fmac_f32_e32 v144, v145, v142
	v_fma_f32 v141, -v141, v144, v143
	v_div_fmas_f32 v141, v141, v142, v144
	v_div_fixup_f32 v248, v141, v140, 1.0
	s_waitcnt vmcnt(0)
; __device__ __forceinline__ float ss_read(const float* ss, int row, int fq) { const f32x4 a = *(const f32x4*)(ss + (unsigned)row * 32 + fq * 8), b = *(const f32x4*)(ss + (unsigned)row * 32 + fq * 8 + 4);
;     float s = ((a[0] + a[1]) + (a[2] + a[3])) + ((b[0] + b[1]) + (b[2] + b[3])); s += __shfl_xor(s, 16); s += __shfl_xor(s, 32); return s; }
;     __device__ __forceinline__ void operator()(const f32x4 (&acc)[2][2][4][2], const Unit& u, int wr, int wc, int fr_, int fq_) const {
;     ...
;                 f32x4 p0, p1; const float rv = 1.0f / sqrtf(ss_read(ss, row0 + ai * HALF + m * 16, fq) * (1.0f / 2048.0f) + 1e-6f);
	v_add_f32_e32 v140, v188, v189
	v_add_f32_e32 v141, v184, v185
	v_add_f32_e32 v142, v186, v187
	v_add_f32_e32 v143, v190, v191
	v_add_f32_e32 v141, v141, v142
	v_add_f32_e32 v140, v140, v143
	v_add_f32_e32 v140, v141, v140
	ds_bpermute_b32 v141, v156, v140
	s_waitcnt lgkmcnt(0)
	v_add_f32_e32 v140, v140, v141
	ds_bpermute_b32 v141, v157, v140
	s_waitcnt lgkmcnt(0)
	v_add_f32_e32 v140, v140, v141
	v_fmamk_f32 v140, v140, 0x3a000000, v225
	v_cmp_gt_f32_e32 vcc, s20, v140
	v_mul_f32_e32 v141, 0x4f800000, v140
	s_nop 0
	v_cndmask_b32_e32 v140, v140, v141, vcc
	v_sqrt_f32_e32 v141, v140
	s_nop 0
	v_add_u32_e32 v142, -1, v141
	v_fma_f32 v143, -v142, v141, v140
	v_cmp_ge_f32_e64 s[0:1], 0, v143
	v_add_u32_e32 v143, 1, v141
	s_nop 0
	v_cndmask_b32_e64 v142, v141, v142, s[0:1]
	v_fma_f32 v141, -v143, v141, v140
	v_cmp_lt_f32_e64 s[0:1], 0, v141
	s_nop 1
	v_cndmask_b32_e64 v141, v142, v143, s[0:1]
	v_mul_f32_e32 v142, 0x37800000, v141
	v_cndmask_b32_e32 v141, v141, v142, vcc
	v_cmp_class_f32_e32 vcc, v140, v226
	s_nop 1
	v_cndmask_b32_e32 v140, v141, v140, vcc
	v_div_scale_f32 v141, s[0:1], v140, v140, 1.0
	v_rcp_f32_e32 v142, v141
	s_nop 0
	v_fma_f32 v143, -v141, v142, 1.0
	v_fmac_f32_e32 v142, v143, v142
	v_div_scale_f32 v143, vcc, 1.0, v140, 1.0
	v_mul_f32_e32 v144, v143, v142
	v_fma_f32 v145, -v141, v144, v143
	v_fmac_f32_e32 v144, v145, v142
	v_fma_f32 v141, -v141, v144, v143
	v_div_fmas_f32 v141, v141, v142, v144
	v_div_fixup_f32 v249, v141, v140, 1.0
	s_mov_b32 s0, 0x4000
	s_mov_b32 s1, 0
	v_lshl_add_u64 v[154:155], v[146:147], 0, s[0:1]
	global_load_dwordx4 v[160:163], v[154:155], off
	global_load_dwordx4 v[164:167], v[154:155], off offset:16
	s_nop 0
	s_mov_b32 s0, 0x4800
	s_mov_b32 s1, 0
	v_lshl_add_u64 v[154:155], v[146:147], 0, s[0:1]
	global_load_dwordx4 v[168:171], v[154:155], off
	global_load_dwordx4 v[172:175], v[154:155], off offset:16
	s_nop 0
	s_mov_b32 s0, 0x5000
	s_mov_b32 s1, 0
	v_lshl_add_u64 v[154:155], v[146:147], 0, s[0:1]
	global_load_dwordx4 v[176:179], v[154:155], off
	global_load_dwordx4 v[180:183], v[154:155], off offset:16
	s_nop 0
	s_mov_b32 s0, 0x5800
	s_mov_b32 s1, 0
	v_lshl_add_u64 v[154:155], v[146:147], 0, s[0:1]
	global_load_dwordx4 v[184:187], v[154:155], off
	global_load_dwordx4 v[188:191], v[154:155], off offset:16
	s_nop 0
	s_waitcnt vmcnt(6)
	v_add_f32_e32 v140, v164, v165
	v_add_f32_e32 v141, v160, v161
	v_add_f32_e32 v142, v162, v163
	v_add_f32_e32 v143, v166, v167
	v_add_f32_e32 v141, v141, v142
	v_add_f32_e32 v140, v140, v143
	v_add_f32_e32 v140, v141, v140
	ds_bpermute_b32 v141, v156, v140
	s_waitcnt lgkmcnt(0)
	v_add_f32_e32 v140, v140, v141
	ds_bpermute_b32 v141, v157, v140
	s_waitcnt lgkmcnt(0)
	v_add_f32_e32 v140, v140, v141
	v_fmamk_f32 v140, v140, 0x3a000000, v225
	v_cmp_gt_f32_e32 vcc, s20, v140
	v_mul_f32_e32 v141, 0x4f800000, v140
	s_nop 0
	v_cndmask_b32_e32 v140, v140, v141, vcc
	v_sqrt_f32_e32 v141, v140
	s_nop 0
	v_add_u32_e32 v142, -1, v141
	v_fma_f32 v143, -v142, v141, v140
	v_cmp_ge_f32_e64 s[0:1], 0, v143
	v_add_u32_e32 v143, 1, v141
	s_nop 0
	v_cndmask_b32_e64 v142, v141, v142, s[0:1]
	v_fma_f32 v141, -v143, v141, v140
	v_cmp_lt_f32_e64 s[0:1], 0, v141
	s_nop 1
	v_cndmask_b32_e64 v141, v142, v143, s[0:1]
	v_mul_f32_e32 v142, 0x37800000, v141
	v_cndmask_b32_e32 v141, v141, v142, vcc
	v_cmp_class_f32_e32 vcc, v140, v226
	s_nop 1
	v_cndmask_b32_e32 v140, v141, v140, vcc
	v_div_scale_f32 v141, s[0:1], v140, v140, 1.0
	v_rcp_f32_e32 v142, v141
	s_nop 0
	v_fma_f32 v143, -v141, v142, 1.0
	v_fmac_f32_e32 v142, v143, v142
	v_div_scale_f32 v143, vcc, 1.0, v140, 1.0
	v_mul_f32_e32 v144, v143, v142
	v_fma_f32 v145, -v141, v144, v143
	v_fmac_f32_e32 v144, v145, v142
	v_fma_f32 v141, -v141, v144, v143
	v_div_fmas_f32 v141, v141, v142, v144
	v_div_fixup_f32 v250, v141, v140, 1.0
	s_waitcnt vmcnt(4)
	v_add_f32_e32 v140, v172, v173
	v_add_f32_e32 v141, v168, v169
	v_add_f32_e32 v142, v170, v171
	v_add_f32_e32 v143, v174, v175
	v_add_f32_e32 v141, v141, v142
	v_add_f32_e32 v140, v140, v143
	v_add_f32_e32 v140, v141, v140
	ds_bpermute_b32 v141, v156, v140
	s_waitcnt lgkmcnt(0)
	v_add_f32_e32 v140, v140, v141
	ds_bpermute_b32 v141, v157, v140
	s_waitcnt lgkmcnt(0)
; __device__ __forceinline__ float ss_read(const float* ss, int row, int fq) { const f32x4 a = *(const f32x4*)(ss + (unsigned)row * 32 + fq * 8), b = *(const f32x4*)(ss + (unsigned)row * 32 + fq * 8 + 4);
;     float s = ((a[0] + a[1]) + (a[2] + a[3])) + ((b[0] + b[1]) + (b[2] + b[3])); s += __shfl_xor(s, 16); s += __shfl_xor(s, 32); return s; }
;     __device__ __forceinline__ void operator()(const f32x4 (&acc)[2][2][4][2], const Unit& u, int wr, int wc, int fr_, int fq_) const {
;     ...
;                 f32x4 p0, p1; const float rv = 1.0f / sqrtf(ss_read(ss, row0 + ai * HALF + m * 16, fq) * (1.0f / 2048.0f) + 1e-6f);
	v_add_f32_e32 v140, v140, v141
	v_fmamk_f32 v140, v140, 0x3a000000, v225
	v_cmp_gt_f32_e32 vcc, s20, v140
	v_mul_f32_e32 v141, 0x4f800000, v140
	s_nop 0
	v_cndmask_b32_e32 v140, v140, v141, vcc
	v_sqrt_f32_e32 v141, v140
	s_nop 0
	v_add_u32_e32 v142, -1, v141
	v_fma_f32 v143, -v142, v141, v140
	v_cmp_ge_f32_e64 s[0:1], 0, v143
	v_add_u32_e32 v143, 1, v141
	s_nop 0
	v_cndmask_b32_e64 v142, v141, v142, s[0:1]
	v_fma_f32 v141, -v143, v141, v140
	v_cmp_lt_f32_e64 s[0:1], 0, v141
	s_nop 1
	v_cndmask_b32_e64 v141, v142, v143, s[0:1]
	v_mul_f32_e32 v142, 0x37800000, v141
	v_cndmask_b32_e32 v141, v141, v142, vcc
	v_cmp_class_f32_e32 vcc, v140, v226
	s_nop 1
	v_cndmask_b32_e32 v140, v141, v140, vcc
	v_div_scale_f32 v141, s[0:1], v140, v140, 1.0
	v_rcp_f32_e32 v142, v141
	s_nop 0
	v_fma_f32 v143, -v141, v142, 1.0
	v_fmac_f32_e32 v142, v143, v142
	v_div_scale_f32 v143, vcc, 1.0, v140, 1.0
	v_mul_f32_e32 v144, v143, v142
	v_fma_f32 v145, -v141, v144, v143
	v_fmac_f32_e32 v144, v145, v142
	v_fma_f32 v141, -v141, v144, v143
	v_div_fmas_f32 v141, v141, v142, v144
	v_div_fixup_f32 v251, v141, v140, 1.0
	s_waitcnt vmcnt(2)
	v_add_f32_e32 v140, v180, v181
	v_add_f32_e32 v141, v176, v177
	v_add_f32_e32 v142, v178, v179
	v_add_f32_e32 v143, v182, v183
	v_add_f32_e32 v141, v141, v142
	v_add_f32_e32 v140, v140, v143
	v_add_f32_e32 v140, v141, v140
	ds_bpermute_b32 v141, v156, v140
	s_waitcnt lgkmcnt(0)
	v_add_f32_e32 v140, v140, v141
	ds_bpermute_b32 v141, v157, v140
	s_waitcnt lgkmcnt(0)
	v_add_f32_e32 v140, v140, v141
	v_fmamk_f32 v140, v140, 0x3a000000, v225
	v_cmp_gt_f32_e32 vcc, s20, v140
	v_mul_f32_e32 v141, 0x4f800000, v140
	s_nop 0
	v_cndmask_b32_e32 v140, v140, v141, vcc
	v_sqrt_f32_e32 v141, v140
	s_nop 0
	v_add_u32_e32 v142, -1, v141
	v_fma_f32 v143, -v142, v141, v140
	v_cmp_ge_f32_e64 s[0:1], 0, v143
	v_add_u32_e32 v143, 1, v141
	s_nop 0
	v_cndmask_b32_e64 v142, v141, v142, s[0:1]
	v_fma_f32 v141, -v143, v141, v140
	v_cmp_lt_f32_e64 s[0:1], 0, v141
	s_nop 1
	v_cndmask_b32_e64 v141, v142, v143, s[0:1]
	v_mul_f32_e32 v142, 0x37800000, v141
	v_cndmask_b32_e32 v141, v141, v142, vcc
	v_cmp_class_f32_e32 vcc, v140, v226
	s_nop 1
	v_cndmask_b32_e32 v140, v141, v140, vcc
	v_div_scale_f32 v141, s[0:1], v140, v140, 1.0
	v_rcp_f32_e32 v142, v141
	s_nop 0
	v_fma_f32 v143, -v141, v142, 1.0
	v_fmac_f32_e32 v142, v143, v142
	v_div_scale_f32 v143, vcc, 1.0, v140, 1.0
	v_mul_f32_e32 v144, v143, v142
	v_fma_f32 v145, -v141, v144, v143
	v_fmac_f32_e32 v144, v145, v142
	v_fma_f32 v141, -v141, v144, v143
	v_div_fmas_f32 v141, v141, v142, v144
	v_div_fixup_f32 v236, v141, v140, 1.0
	s_waitcnt vmcnt(0)
	v_add_f32_e32 v140, v188, v189
	v_add_f32_e32 v141, v184, v185
	v_add_f32_e32 v142, v186, v187
	v_add_f32_e32 v143, v190, v191
	v_add_f32_e32 v141, v141, v142
	v_add_f32_e32 v140, v140, v143
	v_add_f32_e32 v140, v141, v140
	ds_bpermute_b32 v141, v156, v140
	s_waitcnt lgkmcnt(0)
	v_add_f32_e32 v140, v140, v141
	ds_bpermute_b32 v141, v157, v140
	s_waitcnt lgkmcnt(0)
	v_add_f32_e32 v140, v140, v141
	v_fmamk_f32 v140, v140, 0x3a000000, v225
	v_cmp_gt_f32_e32 vcc, s20, v140
	v_mul_f32_e32 v141, 0x4f800000, v140
	s_nop 0
	v_cndmask_b32_e32 v140, v140, v141, vcc
	v_sqrt_f32_e32 v141, v140
	s_nop 0
	v_add_u32_e32 v142, -1, v141
	v_fma_f32 v143, -v142, v141, v140
	v_cmp_ge_f32_e64 s[0:1], 0, v143
	v_add_u32_e32 v143, 1, v141
	s_nop 0
	v_cndmask_b32_e64 v142, v141, v142, s[0:1]
	v_fma_f32 v141, -v143, v141, v140
	v_cmp_lt_f32_e64 s[0:1], 0, v141
	s_nop 1
	v_cndmask_b32_e64 v141, v142, v143, s[0:1]
	v_mul_f32_e32 v142, 0x37800000, v141
	v_cndmask_b32_e32 v141, v141, v142, vcc
	v_cmp_class_f32_e32 vcc, v140, v226
	s_nop 1
	v_cndmask_b32_e32 v140, v141, v140, vcc
	v_div_scale_f32 v141, s[0:1], v140, v140, 1.0
	v_rcp_f32_e32 v142, v141
	s_nop 0
	v_fma_f32 v143, -v141, v142, 1.0
	v_fmac_f32_e32 v142, v143, v142
	v_div_scale_f32 v143, vcc, 1.0, v140, 1.0
	v_mul_f32_e32 v144, v143, v142
	v_fma_f32 v145, -v141, v144, v143
	v_fmac_f32_e32 v144, v145, v142
	v_fma_f32 v141, -v141, v144, v143
	v_div_fmas_f32 v141, v141, v142, v144
	v_div_fixup_f32 v237, v141, v140, 1.0
	s_mov_b32 s101, s59
